# combo + accumulator zeroing via 64-bit moves (halves inter-tile VALU)
# baseline (speedup 1.0000x reference)
; template <class Epi, class Sched, bool ALIGN_EPI = false, bool SP2 = false>
; __device__ __forceinline__ void gemm_phase(PG8_LAS unsigned char* lds, const Gemm g, const Sched& S, const Epi& E, const int tid) {
;     ...
; #pragma unroll
;         for (int a = 0; a < 2; ++a)
; #pragma unroll
;             for (int b = 0; b < 2; ++b)
; #pragma unroll
;                 for (int m = 0; m < 4; ++m)
; #pragma unroll
;                     for (int n = 0; n < 2; ++n) acc[a][b][m][n] = (f32x4){0.f, 0.f, 0.f, 0.f};
;     __device__ __forceinline__ void prefetch(LAS unsigned char* sl, const pg8::Unit& u, int wr, int wc, int lane) const {
;     ...
;         const int col = u.pn * pg8::BM + wc * 32 + (lane & 31) + (lane >> 5) * pg8::HALF; const size_t bo = (size_t)(u.pm / (SEQ / 256)) * MODW;
.LBB0_41:
	s_ashr_i32 s3, s53, 31
	s_lshr_b32 s3, s3, 27
	s_add_i32 s3, s53, s3
	s_lshl_b32 s54, s20, 8
	s_ashr_i32 s3, s3, 5
	v_or_b32_e32 v132, s54, v226
	s_add_u32 s55, s18, 0x100
	v_mov_b32_e32 v4, 0
	s_mul_hi_i32 s50, s3, 0x12000
	s_mul_i32 s51, s3, 0x12000
	v_ashrrev_i32_e32 v133, 31, v132
	s_addc_u32 s74, s19, 0
	s_mov_b32 s75, -2
	v_mov_b32_e32 v5, v4
	v_mov_b64_e32 v[6:7], 0
	v_mov_b64_e32 v[8:9], 0
	v_mov_b64_e32 v[10:11], 0
	v_mov_b64_e32 v[20:21], 0
	v_mov_b64_e32 v[22:23], 0
	v_mov_b64_e32 v[24:25], 0
	v_mov_b64_e32 v[26:27], 0
	s_waitcnt vmcnt(0)
	v_mov_b64_e32 v[36:37], 0
	v_mov_b64_e32 v[38:39], 0
	v_mov_b64_e32 v[40:41], 0
	v_mov_b64_e32 v[42:43], 0
	v_mov_b64_e32 v[52:53], 0
	v_mov_b64_e32 v[54:55], 0
	v_mov_b64_e32 v[56:57], 0
	v_mov_b64_e32 v[58:59], 0
	v_mov_b64_e32 v[12:13], 0
	v_mov_b64_e32 v[14:15], 0
	v_mov_b64_e32 v[16:17], 0
	v_mov_b64_e32 v[18:19], 0
	v_mov_b64_e32 v[28:29], 0
	v_mov_b64_e32 v[30:31], 0
	v_mov_b64_e32 v[32:33], 0
	v_mov_b64_e32 v[34:35], 0
	v_mov_b64_e32 v[44:45], 0
	v_mov_b64_e32 v[46:47], 0
	v_mov_b64_e32 v[48:49], 0
	v_mov_b64_e32 v[50:51], 0
	v_mov_b64_e32 v[60:61], 0
	v_mov_b64_e32 v[62:63], 0
	v_mov_b64_e32 v[64:65], 0
	v_mov_b64_e32 v[66:67], 0
	v_mov_b64_e32 v[68:69], 0
	v_mov_b64_e32 v[70:71], 0
	v_mov_b64_e32 v[72:73], 0
	v_mov_b64_e32 v[74:75], 0
	v_mov_b64_e32 v[84:85], 0
	v_mov_b64_e32 v[86:87], 0
	v_mov_b64_e32 v[88:89], 0
	v_mov_b64_e32 v[90:91], 0
	v_mov_b64_e32 v[100:101], 0
	v_mov_b64_e32 v[102:103], 0
	v_mov_b64_e32 v[104:105], 0
	v_mov_b64_e32 v[106:107], 0
	v_mov_b64_e32 v[116:117], 0
	v_mov_b64_e32 v[118:119], 0
	v_mov_b64_e32 v[120:121], 0
	v_mov_b64_e32 v[122:123], 0
	v_mov_b64_e32 v[76:77], 0
	v_mov_b64_e32 v[78:79], 0
	v_mov_b64_e32 v[80:81], 0
	v_mov_b64_e32 v[82:83], 0
	v_mov_b64_e32 v[92:93], 0
	v_mov_b64_e32 v[94:95], 0
	v_mov_b64_e32 v[96:97], 0
	v_mov_b64_e32 v[98:99], 0
	v_mov_b64_e32 v[108:109], 0
	v_mov_b64_e32 v[110:111], 0
	v_mov_b64_e32 v[112:113], 0
	v_mov_b64_e32 v[114:115], 0
	v_mov_b64_e32 v[124:125], 0
	v_mov_b64_e32 v[126:127], 0
	v_mov_b64_e32 v[128:129], 0
	v_mov_b64_e32 v[130:131], 0
	s_branch .LBB0_43

; template <class Epi, class Sched, bool ALIGN_EPI = false, bool SP2 = false>
; __device__ __forceinline__ void gemm_phase(PG8_LAS unsigned char* lds, const Gemm g, const Sched& S, const Epi& E, const int tid) {
;     ...
;         const bool has_next = S.next(ui + 1, nxt);
;         const char* nA = has_next ? (const char*)g.A + (size_t)nxt.pm * tstep : cA; const char* nB = has_next ? (const char*)g.Bt + (size_t)nxt.pn * tstep : cB;
;     ...
; #pragma unroll
;         for (int a = 0; a < 2; ++a)
; #pragma unroll
;             for (int b = 0; b < 2; ++b)
; #pragma unroll
;                 for (int m = 0; m < 4; ++m)
; #pragma unroll
;                     for (int n = 0; n < 2; ++n) acc[a][b][m][n] = (f32x4){0.f, 0.f, 0.f, 0.f};
;     __device__ __forceinline__ void prefetch(LAS unsigned char* sl, const pg8::Unit& u, int wr, int wc, int lane) const {
;     ...
;         const int col = u.pn * pg8::BM + wc * 32 + (lane & 31) + (lane >> 5) * pg8::HALF; const size_t bo = (size_t)(u.pm / (SEQ / 256)) * MODW;
.LBB0_73:
	s_ashr_i32 s17, s16, 31
	s_lshl_b64 s[18:19], s[16:17], 20
	s_add_u32 s18, s5, s18
	s_addc_u32 s19, s37, s19
	s_and_b64 s[20:21], s[8:9], exec
	s_cselect_b32 s17, s19, s29
	s_cselect_b32 s23, s18, s28
	s_ashr_i32 s15, s14, 31
	s_lshl_b64 s[20:21], s[14:15], 20
	s_add_u32 s20, s39, s20
	s_addc_u32 s21, s44, s21
	s_and_b64 s[30:31], s[8:9], exec
	s_cselect_b32 s99, s21, s27
	s_cselect_b32 vcc_lo, s20, s26
	s_lshl_b32 s15, s24, 8
	s_ashr_i32 s24, s22, 31
	s_lshr_b32 s24, s24, 27
	s_add_i32 s24, s22, s24
	s_ashr_i32 s24, s24, 5
	s_mul_hi_i32 s31, s24, 0x4800
	s_mul_i32 s30, s24, 0x4800
	s_add_u32 s24, s28, 0x80080
	v_or_b32_e32 v6, s15, v249
	s_addc_u32 s25, s29, 0
	v_ashrrev_i32_e32 v7, 31, v6
	s_add_u32 vcc_hi, s26, 0x100
	v_mov_b32_e32 v4, 0
	s_addc_u32 s50, s27, 0
	s_mov_b32 s51, -2
	s_lshl_b64 s[26:27], s[30:31], 2
	v_lshlrev_b64 v[96:97], 2, v[6:7]
	v_mov_b32_e32 v5, v4
	v_mov_b64_e32 v[6:7], 0
	v_mov_b64_e32 v[8:9], 0
	v_mov_b64_e32 v[10:11], 0
	v_mov_b64_e32 v[20:21], 0
	v_mov_b64_e32 v[22:23], 0
	v_mov_b64_e32 v[24:25], 0
	v_mov_b64_e32 v[26:27], 0
	s_waitcnt vmcnt(0)
	v_mov_b64_e32 v[36:37], 0
	v_mov_b64_e32 v[38:39], 0
	v_mov_b64_e32 v[40:41], 0
	v_mov_b64_e32 v[42:43], 0
	v_mov_b64_e32 v[52:53], 0
	v_mov_b64_e32 v[54:55], 0
	v_mov_b64_e32 v[56:57], 0
	v_mov_b64_e32 v[58:59], 0
	v_mov_b64_e32 v[12:13], 0
	v_mov_b64_e32 v[14:15], 0
	v_mov_b64_e32 v[16:17], 0
	v_mov_b64_e32 v[18:19], 0
	v_mov_b64_e32 v[28:29], 0
	v_mov_b64_e32 v[30:31], 0
	v_mov_b64_e32 v[32:33], 0
	v_mov_b64_e32 v[34:35], 0
	v_mov_b64_e32 v[44:45], 0
	v_mov_b64_e32 v[46:47], 0
	v_mov_b64_e32 v[48:49], 0
	v_mov_b64_e32 v[50:51], 0
	v_mov_b64_e32 v[60:61], 0
	v_mov_b64_e32 v[62:63], 0
	v_mov_b64_e32 v[64:65], 0
	v_mov_b64_e32 v[66:67], 0
	v_mov_b64_e32 v[68:69], 0
	v_mov_b64_e32 v[70:71], 0
	v_mov_b64_e32 v[72:73], 0
	v_mov_b64_e32 v[74:75], 0
	v_mov_b64_e32 v[84:85], 0
	v_mov_b64_e32 v[86:87], 0
	v_mov_b64_e32 v[88:89], 0
	v_mov_b64_e32 v[90:91], 0
	v_mov_b64_e32 v[116:117], 0
	v_mov_b64_e32 v[118:119], 0
	v_mov_b64_e32 v[120:121], 0
	v_mov_b64_e32 v[122:123], 0
	v_mov_b64_e32 v[132:133], 0
	v_mov_b64_e32 v[134:135], 0
	v_mov_b64_e32 v[136:137], 0
	v_mov_b64_e32 v[138:139], 0
	v_mov_b64_e32 v[76:77], 0
	v_mov_b64_e32 v[78:79], 0
	v_mov_b64_e32 v[80:81], 0
	v_mov_b64_e32 v[82:83], 0
	v_mov_b64_e32 v[92:93], 0
	v_mov_b64_e32 v[94:95], 0
	v_mov_b64_e32 v[112:113], 0
	v_mov_b64_e32 v[114:115], 0
	v_mov_b64_e32 v[124:125], 0
	v_mov_b64_e32 v[126:127], 0
	v_mov_b64_e32 v[128:129], 0
	v_mov_b64_e32 v[130:131], 0
	v_mov_b64_e32 v[140:141], 0
	v_mov_b64_e32 v[142:143], 0
	v_mov_b64_e32 v[148:149], 0
	v_mov_b64_e32 v[150:151], 0
	s_branch .LBB0_75

;     __device__ __forceinline__ void prefetch(PG8_LAS unsigned char* sl, const Unit& u, int wr, int wc, int lane) const {
;     ...
;         const float* bp = bias2 + (size_t)(u.pm / tiles_per_batch) * bias_stride + u.pn * BM + wc * 32 + (lane & 31) + (lane >> 5) * HALF;
; template <class Epi, class Sched, bool ALIGN_EPI = false, bool SP2 = false>
; __device__ __forceinline__ void gemm_phase(PG8_LAS unsigned char* lds, const Gemm g, const Sched& S, const Epi& E, const int tid) {
;     ...
;         const bool has_next = S.next(ui + 1, nxt);
;         const char* nA = has_next ? (const char*)g.A + (size_t)nxt.pm * tstep : cA; const char* nB = has_next ? (const char*)g.Bt + (size_t)nxt.pn * tstep : cB;
;     ...
; #pragma unroll
;         for (int a = 0; a < 2; ++a)
; #pragma unroll
;             for (int b = 0; b < 2; ++b)
; #pragma unroll
;                 for (int m = 0; m < 4; ++m)
; #pragma unroll
;                     for (int n = 0; n < 2; ++n) acc[a][b][m][n] = (f32x4){0.f, 0.f, 0.f, 0.f};
.LBB0_155:
	s_ashr_i32 s17, s16, 31
	s_lshl_b64 s[18:19], s[16:17], 20
	s_add_u32 s18, s90, s18
	s_addc_u32 s19, s91, s19
	s_and_b64 s[20:21], s[6:7], exec
	s_cselect_b32 s9, s19, s31
	s_cselect_b32 s17, s18, s30
	s_ashr_i32 s15, s14, 31
	s_lshl_b64 s[20:21], s[14:15], 20
	s_add_u32 s20, s36, s20
	s_addc_u32 s21, s37, s21
	s_and_b64 s[22:23], s[6:7], exec
	s_cselect_b32 s15, s21, s29
	s_cselect_b32 s39, s20, s28
	s_ashr_i32 s3, s26, 31
	s_lshl_b32 s24, s8, 8
	s_lshr_b32 s3, s3, 27
	s_ashr_i32 s25, s24, 31
	s_add_i32 s3, s26, s3
	s_lshl_b32 s22, s26, 8
	v_lshl_add_u64 v[4:5], s[24:25], 2, v[152:153]
	s_ashr_i32 s3, s3, 5
	v_mov_b32_e32 v6, 0x3400
	s_ashr_i32 s23, s22, 31
	v_mad_i64_i32 v[32:33], s[26:27], s3, v6, v[4:5]
	s_add_u32 s26, s30, 0x80080
	s_addc_u32 s27, s31, 0
	v_lshl_add_u64 v[28:29], s[22:23], 2, v[154:155]
	s_add_u32 s23, s28, 0x100
	v_mov_b32_e32 v4, 0
	v_lshl_add_u64 v[30:31], v[28:29], 0, s[56:57]
	s_addc_u32 s25, s29, 0
	s_mov_b32 s50, -2
	v_mov_b32_e32 v5, v4
	v_mov_b64_e32 v[6:7], 0
	v_mov_b64_e32 v[8:9], 0
	v_mov_b64_e32 v[10:11], 0
	v_mov_b64_e32 v[20:21], 0
	v_mov_b64_e32 v[22:23], 0
	v_mov_b64_e32 v[24:25], 0
	v_mov_b64_e32 v[26:27], 0
	v_mov_b64_e32 v[52:53], 0
	v_mov_b64_e32 v[54:55], 0
	v_mov_b64_e32 v[56:57], 0
	v_mov_b64_e32 v[58:59], 0
	v_mov_b64_e32 v[68:69], 0
	v_mov_b64_e32 v[70:71], 0
	v_mov_b64_e32 v[72:73], 0
	v_mov_b64_e32 v[74:75], 0
	v_mov_b64_e32 v[12:13], 0
	v_mov_b64_e32 v[14:15], 0
	v_mov_b64_e32 v[16:17], 0
	v_mov_b64_e32 v[18:19], 0
	v_mov_b64_e32 v[36:37], 0
	v_mov_b64_e32 v[38:39], 0
	v_mov_b64_e32 v[40:41], 0
	v_mov_b64_e32 v[42:43], 0
	v_mov_b64_e32 v[60:61], 0
	v_mov_b64_e32 v[62:63], 0
	v_mov_b64_e32 v[64:65], 0
	v_mov_b64_e32 v[66:67], 0
	v_mov_b64_e32 v[76:77], 0
	v_mov_b64_e32 v[78:79], 0
	v_mov_b64_e32 v[80:81], 0
	v_mov_b64_e32 v[82:83], 0
	v_mov_b64_e32 v[84:85], 0
	v_mov_b64_e32 v[86:87], 0
	v_mov_b64_e32 v[88:89], 0
	v_mov_b64_e32 v[90:91], 0
	v_mov_b64_e32 v[100:101], 0
	v_mov_b64_e32 v[102:103], 0
	v_mov_b64_e32 v[104:105], 0
	v_mov_b64_e32 v[106:107], 0
	v_mov_b64_e32 v[116:117], 0
	v_mov_b64_e32 v[118:119], 0
	v_mov_b64_e32 v[120:121], 0
	v_mov_b64_e32 v[122:123], 0
	v_mov_b64_e32 v[132:133], 0
	v_mov_b64_e32 v[134:135], 0
	v_mov_b64_e32 v[136:137], 0
	v_mov_b64_e32 v[138:139], 0
	v_mov_b64_e32 v[92:93], 0
	v_mov_b64_e32 v[94:95], 0
	v_mov_b64_e32 v[96:97], 0
	v_mov_b64_e32 v[98:99], 0
	v_mov_b64_e32 v[108:109], 0
	v_mov_b64_e32 v[110:111], 0
	v_mov_b64_e32 v[112:113], 0
	v_mov_b64_e32 v[114:115], 0
	v_mov_b64_e32 v[124:125], 0
	v_mov_b64_e32 v[126:127], 0
	v_mov_b64_e32 v[128:129], 0
	v_mov_b64_e32 v[130:131], 0
	v_mov_b64_e32 v[140:141], 0
	v_mov_b64_e32 v[142:143], 0
	v_mov_b64_e32 v[144:145], 0
	v_mov_b64_e32 v[146:147], 0
	s_branch .LBB0_157

; template <class Epi, class Sched, bool ALIGN_EPI = false, bool SP2 = false>
; __device__ __forceinline__ void gemm_phase(PG8_LAS unsigned char* lds, const Gemm g, const Sched& S, const Epi& E, const int tid) {
;     ...
; #pragma unroll
;         for (int a = 0; a < 2; ++a)
; #pragma unroll
;             for (int b = 0; b < 2; ++b)
; #pragma unroll
;                 for (int m = 0; m < 4; ++m)
; #pragma unroll
;                     for (int n = 0; n < 2; ++n) acc[a][b][m][n] = (f32x4){0.f, 0.f, 0.f, 0.f};
;     __device__ __forceinline__ void prefetch(LAS unsigned char* sl, const pg8::Unit& u, int wr, int wc, int lane) const {
;     ...
;         const int col = u.pn * pg8::BM + wc * 32 + (lane & 31) + (lane >> 5) * pg8::HALF; const size_t bo = (size_t)(u.pm / (SEQ / 256)) * MODW;
.LBB0_227:
	s_lshl_b32 s71, s22, 8
	s_ashr_i32 s22, s63, 31
	s_lshr_b32 s22, s22, 27
	s_add_i32 s22, s63, s22
	v_or_b32_e32 v6, s71, v222
	s_ashr_i32 s22, s22, 5
	s_mul_hi_i32 s23, s22, 0x4800
	s_mulk_i32 s22, 0x4800
	v_ashrrev_i32_e32 v7, 31, v6
	s_add_u32 s74, s18, 0x100
	v_mov_b32_e32 v4, 0
	s_addc_u32 s75, s19, 0
	s_mov_b32 s84, -2
	s_lshl_b64 s[18:19], s[22:23], 2
	v_lshlrev_b64 v[132:133], 2, v[6:7]
	v_mov_b32_e32 v5, v4
	v_mov_b64_e32 v[6:7], 0
	v_mov_b64_e32 v[8:9], 0
	v_mov_b64_e32 v[10:11], 0
	v_mov_b64_e32 v[20:21], 0
	v_mov_b64_e32 v[22:23], 0
	v_mov_b64_e32 v[24:25], 0
	v_mov_b64_e32 v[26:27], 0
	s_waitcnt vmcnt(0)
	v_mov_b64_e32 v[36:37], 0
	v_mov_b64_e32 v[38:39], 0
	v_mov_b64_e32 v[40:41], 0
	v_mov_b64_e32 v[42:43], 0
	v_mov_b64_e32 v[52:53], 0
	v_mov_b64_e32 v[54:55], 0
	v_mov_b64_e32 v[56:57], 0
	v_mov_b64_e32 v[58:59], 0
	v_mov_b64_e32 v[12:13], 0
	v_mov_b64_e32 v[14:15], 0
	v_mov_b64_e32 v[16:17], 0
	v_mov_b64_e32 v[18:19], 0
	v_mov_b64_e32 v[28:29], 0
	v_mov_b64_e32 v[30:31], 0
	v_mov_b64_e32 v[32:33], 0
	v_mov_b64_e32 v[34:35], 0
	v_mov_b64_e32 v[44:45], 0
	v_mov_b64_e32 v[46:47], 0
	v_mov_b64_e32 v[48:49], 0
	v_mov_b64_e32 v[50:51], 0
	v_mov_b64_e32 v[60:61], 0
	v_mov_b64_e32 v[62:63], 0
	v_mov_b64_e32 v[64:65], 0
	v_mov_b64_e32 v[66:67], 0
	v_mov_b64_e32 v[68:69], 0
	v_mov_b64_e32 v[70:71], 0
	v_mov_b64_e32 v[72:73], 0
	v_mov_b64_e32 v[74:75], 0
	v_mov_b64_e32 v[84:85], 0
	v_mov_b64_e32 v[86:87], 0
	v_mov_b64_e32 v[88:89], 0
	v_mov_b64_e32 v[90:91], 0
	v_mov_b64_e32 v[100:101], 0
	v_mov_b64_e32 v[102:103], 0
	v_mov_b64_e32 v[104:105], 0
	v_mov_b64_e32 v[106:107], 0
	v_mov_b64_e32 v[116:117], 0
	v_mov_b64_e32 v[118:119], 0
	v_mov_b64_e32 v[120:121], 0
	v_mov_b64_e32 v[122:123], 0
	v_mov_b64_e32 v[76:77], 0
	v_mov_b64_e32 v[78:79], 0
	v_mov_b64_e32 v[80:81], 0
	v_mov_b64_e32 v[82:83], 0
	v_mov_b64_e32 v[92:93], 0
	v_mov_b64_e32 v[94:95], 0
	v_mov_b64_e32 v[96:97], 0
	v_mov_b64_e32 v[98:99], 0
	v_mov_b64_e32 v[108:109], 0
	v_mov_b64_e32 v[110:111], 0
	v_mov_b64_e32 v[112:113], 0
	v_mov_b64_e32 v[114:115], 0
	v_mov_b64_e32 v[124:125], 0
	v_mov_b64_e32 v[126:127], 0
	v_mov_b64_e32 v[128:129], 0
	v_mov_b64_e32 v[130:131], 0
	s_branch .LBB0_229

;     __device__ __forceinline__ void prefetch(PG8_LAS unsigned char* sl, const Unit& u, int wr, int wc, int lane) const {
;     ...
;         const float* bp = bias2 + (size_t)(u.pm / tiles_per_batch) * bias_stride + u.pn * BM + wc * 32 + (lane & 31) + (lane >> 5) * HALF;
; template <class Epi, class Sched, bool ALIGN_EPI = false, bool SP2 = false>
; __device__ __forceinline__ void gemm_phase(PG8_LAS unsigned char* lds, const Gemm g, const Sched& S, const Epi& E, const int tid) {
;     ...
;         const bool has_next = S.next(ui + 1, nxt);
;         const char* nA = has_next ? (const char*)g.A + (size_t)nxt.pm * tstep : cA; const char* nB = has_next ? (const char*)g.Bt + (size_t)nxt.pn * tstep : cB;
;     ...
; #pragma unroll
;         for (int a = 0; a < 2; ++a)
; #pragma unroll
;             for (int b = 0; b < 2; ++b)
; #pragma unroll
;                 for (int m = 0; m < 4; ++m)
; #pragma unroll
;                     for (int n = 0; n < 2; ++n) acc[a][b][m][n] = (f32x4){0.f, 0.f, 0.f, 0.f};
.LBB0_265:
	s_ashr_i32 s17, s16, 31
	s_lshl_b64 s[18:19], s[16:17], 20
	s_add_u32 s18, s90, s18
	s_addc_u32 s19, s91, s19
	s_and_b64 s[20:21], s[6:7], exec
	s_cselect_b32 s17, s19, s29
	s_cselect_b32 s75, s18, s28
	s_ashr_i32 s15, s14, 31
	s_lshl_b64 s[20:21], s[14:15], 20
	s_add_u32 s20, s5, s20
	s_addc_u32 s21, s30, s21
	s_and_b64 s[22:23], s[6:7], exec
	s_cselect_b32 s15, s21, s27
	s_cselect_b32 s85, s20, s26
	s_lshl_b32 s22, s24, 8
	s_ashr_i32 s23, s22, 31
	v_lshl_add_u64 v[128:129], s[22:23], 2, v[154:155]
	s_ashr_i32 s23, s24, 31
	s_lshl_b32 s50, s74, 8
	s_lshr_b32 s23, s23, 27
	s_ashr_i32 s51, s50, 31
	s_add_i32 s23, s24, s23
	v_lshl_add_u64 v[4:5], s[50:51], 2, v[152:153]
	s_ashr_i32 s23, s23, 5
	v_mad_i64_i32 v[132:133], s[24:25], s23, v235, v[4:5]
	s_add_u32 s24, s28, 0x80080
	s_addc_u32 s25, s29, 0
	s_add_u32 s23, s26, 0x100
	v_mov_b32_e32 v4, 0
	v_lshl_add_u64 v[130:131], v[128:129], 0, s[56:57]
	s_addc_u32 s50, s27, 0
	s_mov_b32 s51, -2
	v_mov_b32_e32 v5, v4
	v_mov_b64_e32 v[6:7], 0
	v_mov_b64_e32 v[8:9], 0
	v_mov_b64_e32 v[10:11], 0
	v_mov_b64_e32 v[20:21], 0
	v_mov_b64_e32 v[22:23], 0
	v_mov_b64_e32 v[24:25], 0
	v_mov_b64_e32 v[26:27], 0
	v_mov_b64_e32 v[36:37], 0
	v_mov_b64_e32 v[38:39], 0
	v_mov_b64_e32 v[40:41], 0
	v_mov_b64_e32 v[42:43], 0
	v_mov_b64_e32 v[52:53], 0
	v_mov_b64_e32 v[54:55], 0
	v_mov_b64_e32 v[56:57], 0
	v_mov_b64_e32 v[58:59], 0
	v_mov_b64_e32 v[12:13], 0
	v_mov_b64_e32 v[14:15], 0
	v_mov_b64_e32 v[16:17], 0
	v_mov_b64_e32 v[18:19], 0
	v_mov_b64_e32 v[28:29], 0
	v_mov_b64_e32 v[30:31], 0
	v_mov_b64_e32 v[32:33], 0
	v_mov_b64_e32 v[34:35], 0
	v_mov_b64_e32 v[44:45], 0
	v_mov_b64_e32 v[46:47], 0
	v_mov_b64_e32 v[48:49], 0
	v_mov_b64_e32 v[50:51], 0
	v_mov_b64_e32 v[60:61], 0
	v_mov_b64_e32 v[62:63], 0
	v_mov_b64_e32 v[64:65], 0
	v_mov_b64_e32 v[66:67], 0
	v_mov_b64_e32 v[68:69], 0
	v_mov_b64_e32 v[70:71], 0
	v_mov_b64_e32 v[72:73], 0
	v_mov_b64_e32 v[74:75], 0
	v_mov_b64_e32 v[84:85], 0
	v_mov_b64_e32 v[86:87], 0
	v_mov_b64_e32 v[88:89], 0
	v_mov_b64_e32 v[90:91], 0
	v_mov_b64_e32 v[100:101], 0
	v_mov_b64_e32 v[102:103], 0
	v_mov_b64_e32 v[104:105], 0
	v_mov_b64_e32 v[106:107], 0
	v_mov_b64_e32 v[116:117], 0
	v_mov_b64_e32 v[118:119], 0
	v_mov_b64_e32 v[120:121], 0
	v_mov_b64_e32 v[122:123], 0
	v_mov_b64_e32 v[76:77], 0
	v_mov_b64_e32 v[78:79], 0
	v_mov_b64_e32 v[80:81], 0
	v_mov_b64_e32 v[82:83], 0
	v_mov_b64_e32 v[92:93], 0
	v_mov_b64_e32 v[94:95], 0
	v_mov_b64_e32 v[96:97], 0
	v_mov_b64_e32 v[98:99], 0
	v_mov_b64_e32 v[108:109], 0
	v_mov_b64_e32 v[110:111], 0
	v_mov_b64_e32 v[112:113], 0
	v_mov_b64_e32 v[114:115], 0
	v_mov_b64_e32 v[124:125], 0
	v_mov_b64_e32 v[126:127], 0
	v_mov_b64_e32 v[136:137], 0
	v_mov_b64_e32 v[138:139], 0
	s_branch .LBB0_267

; #define LDS_WAIT() asm volatile("s_waitcnt lgkmcnt(0)" ::: "memory")
; __device__ __forceinline__ void mod_item(KA a, int it, LAS float* scr, int lane) {
;     const int cgp = it % N_MODCG, kc = it / N_MODCG, k0 = kc * KCH;
;     const float* c = a->in[I_C];
;     { const int kk = lane & 31, bh = lane >> 5;
; #pragma unroll
;       for (int bb = 0; bb < 2; ++bb) { const int b = bh * 2 + bb; const float v = c[b * DM + k0 + kk]; scr[b * 32 + kk] = v / (1.0f + __expf(-v)); } }
;     LDS_WAIT(); asm volatile("" ::: "memory");
;     const float* wp = a->in[I_WADA] + (size_t)k0 * MODW + cgp * 256 + lane * 4;
;     f32x4 acc[4] = {{0.f, 0.f, 0.f, 0.f}, {0.f, 0.f, 0.f, 0.f}, {0.f, 0.f, 0.f, 0.f}, {0.f, 0.f, 0.f, 0.f}};
.LBB0_406:
	s_andn2_b64 vcc, exec, s[6:7]
	s_cbranch_vccnz .LBB0_359
	s_mul_hi_i32 s6, s12, 0x38e38e39
	s_lshr_b32 s7, s6, 31
	s_ashr_i32 s13, s6, 4
	s_add_i32 s13, s13, s7
	s_load_dwordx4 s[8:11], s[82:83], 0x8
	s_lshl_b32 s6, s13, 5
	v_or_b32_e32 v2, s6, v0
	v_add_u32_e32 v4, v2, v50
	v_ashrrev_i32_e32 v5, 31, v4
	v_add_u32_e32 v6, v2, v51
	s_waitcnt lgkmcnt(0)
	v_lshl_add_u64 v[4:5], v[4:5], 2, s[8:9]
	v_ashrrev_i32_e32 v7, 31, v6
	v_lshl_add_u64 v[6:7], v[6:7], 2, s[8:9]
	global_load_dword v2, v[4:5], off
	global_load_dword v16, v[6:7], off
	s_mul_i32 s7, s13, 0x48
	s_mul_i32 s15, s13, 0x240000
	s_sub_i32 s7, s12, s7
	s_mul_hi_i32 s6, s6, 0x12000
	s_add_u32 s15, s10, s15
	s_addc_u32 s16, s11, s6
	s_lshl_b32 s10, s7, 8
	s_ashr_i32 s11, s10, 31
	s_lshl_b64 s[6:7], s[10:11], 2
	s_add_u32 s6, s15, s6
	v_mov_b32_e32 v41, v3
	s_addc_u32 s7, s16, s7
	v_lshl_add_u64 v[42:43], s[6:7], 0, v[40:41]
	v_mov_b32_e32 v4, 0
	s_mov_b64 s[8:9], 0
	s_mov_b32 s14, s2
	v_mov_b32_e32 v5, v4
	v_mov_b64_e32 v[6:7], 0
	v_mov_b64_e32 v[8:9], 0
	v_mov_b64_e32 v[10:11], 0
	v_mov_b64_e32 v[12:13], 0
	v_mov_b64_e32 v[14:15], 0
	s_waitcnt vmcnt(1)
	v_mul_f32_e32 v17, 0xbfb8aa3b, v2
	s_waitcnt vmcnt(0)
	v_mul_f32_e32 v18, 0xbfb8aa3b, v16
	v_exp_f32_e32 v17, v17
	v_exp_f32_e32 v18, v18
	v_add_f32_e32 v17, 1.0, v17
	v_add_f32_e32 v18, 1.0, v18
	v_div_scale_f32 v19, s[6:7], v17, v17, v2
	v_div_scale_f32 v44, s[6:7], v18, v18, v16
	v_rcp_f32_e32 v45, v19
	v_rcp_f32_e32 v62, v44
	v_div_scale_f32 v41, vcc, v2, v17, v2
	v_fma_f32 v64, -v19, v45, 1.0
	v_fma_f32 v65, -v44, v62, 1.0
	v_fmac_f32_e32 v45, v64, v45
	v_div_scale_f32 v63, s[6:7], v16, v18, v16
	v_fmac_f32_e32 v62, v65, v62
	v_mul_f32_e32 v64, v41, v45
	v_mul_f32_e32 v65, v63, v62
	v_fma_f32 v66, -v19, v64, v41
	v_fma_f32 v67, -v44, v65, v63
	v_fmac_f32_e32 v64, v66, v45
	v_fmac_f32_e32 v65, v67, v62
	v_fma_f32 v19, -v19, v64, v41
	v_fma_f32 v41, -v44, v65, v63
	v_div_fmas_f32 v19, v19, v45, v64
	s_mov_b64 vcc, s[6:7]
	v_div_fixup_f32 v2, v19, v17, v2
	v_div_fmas_f32 v17, v41, v62, v65
	ds_write_b32 v60, v2
	v_div_fixup_f32 v2, v17, v18, v16
	ds_write_b32 v61, v2
	s_waitcnt lgkmcnt(0)
	v_mov_b32_e32 v16, v4
	v_mov_b32_e32 v17, v4
	v_mov_b32_e32 v18, v4
	v_mov_b32_e32 v19, v4
